# IDX score loop: relu-weighted head sum cut from 4 to 2 VALU ops per accumulator element (NaN-canonicalise dropped, 1/8 scale folded exactly into the weights) and all B fragments of a half read up fron
# speedup vs baseline: 1.0078x; 1.0075x over previous
; #define LAS __attribute__((address_space(3)))
; __device__ __forceinline__ void idx_unit(bf16* QB, float* SC, int* SEL, const float* qg, const float* kg, int b, int tp, LAS unsigned char* wl, int lane, bool do_norm) {
;     ...
;         bf16x8 af[2][4];
; #pragma unroll
;         for (int q2 = 0; q2 < 2; ++q2) { const bf16* ap = QB + (row + 2 * q2 + (n >> 4)) * NBP + CQI + (n & 15) * 64 + 8 * hi;
; #pragma unroll
;           for (int ks = 0; ks < 4; ++ks) af[q2][ks] = *(const bf16x8*)(ap + 16 * ks); }
;         float w[4][8];
; #pragma unroll
;         for (int a = 0; a < 4; ++a)
; #pragma unroll
;             for (int r = 0; r < 8; ++r) { const int hh = (r & 3) + 8 * (r >> 2) + 4 * hi; w[a][r] = 0.25f * bflo((unsigned)QB[(row + a) * NBP + CWI + hh]); }
;         float* scw0 = SC + (row + hi) * SEQ + n; float* scw1 = scw0 + 2 * (size_t)SEQ;
;         const int r8 = lane >> 3, c8 = lane & 7;
;         const bf16* kg8 = QB + (rowbase + r8) * NBP + CKI + c8 * 8;
;         LAS unsigned char* sdst = wl + r8 * 144 + c8 * 16;
;         const LAS unsigned char* fsrc = wl + n * 144 + 16 * hi;
;         bf16x8 cur[8];
; #pragma unroll
;         for (int i = 0; i < 8; ++i) cur[i] = *(const bf16x8*)(kg8 + (size_t)(8 * i) * NBP);
.LBB0_241:
	s_and_b64 vcc, exec, s[4:5]
	v_writelane_b32 v250, s11, 33
	s_cbranch_vccz .LBB0_561
	v_readlane_b32 s8, v253, 53
	v_readlane_b32 s9, v253, 54
	v_or_b32_e32 v2, s2, v108
	s_movk_i32 s11, 0x2200
	v_mov_b64_e32 v[0:1], s[8:9]
	v_mad_u64_u32 v[2:3], s[4:5], v2, s11, v[0:1]
	v_mad_i32_i24 v3, s79, v212, v3
	v_lshl_add_u64 v[2:3], v[2:3], 0, v[182:183]
	v_lshl_add_u64 v[2:3], v[2:3], 0, v[128:129]
	s_mov_b64 s[12:13], 0x1800
	v_lshl_add_u64 v[4:5], v[2:3], 0, s[12:13]
	v_add_co_u32_e32 v2, vcc, 0x1000, v2
	v_lshl_add_u64 v[18:19], s[0:1], 0, v[114:115]
	s_nop 0
	v_addc_co_u32_e32 v3, vcc, 0, v3, vcc
	global_load_dwordx4 v[32:35], v[4:5], off offset:32
	global_load_dwordx4 v[36:39], v[4:5], off offset:64
	global_load_dwordx4 v[40:43], v[2:3], off offset:2048
	global_load_dwordx4 v[44:47], v[4:5], off offset:96
	v_or_b32_e32 v2, s2, v110
	v_mad_u64_u32 v[2:3], s[4:5], v2, s11, v[0:1]
	v_mad_i32_i24 v3, s79, v212, v3
	v_lshl_add_u64 v[2:3], v[2:3], 0, v[182:183]
	v_lshl_add_u64 v[2:3], v[2:3], 0, v[128:129]
	s_movk_i32 s4, 0x1000
	v_lshl_add_u64 v[4:5], v[2:3], 0, s[12:13]
	v_add_co_u32_e32 v2, vcc, s4, v2
	s_mul_i32 s4, s79, 0x2200
	s_mul_hi_u32 s5, s2, 0x2200
	s_add_i32 s5, s5, s4
	s_mul_i32 s4, s2, 0x2200
	s_add_u32 s4, s8, s4
	v_addc_co_u32_e32 v3, vcc, 0, v3, vcc
	s_addc_u32 s5, s9, s5
	global_load_dwordx4 v[48:51], v[4:5], off offset:32
	global_load_dwordx4 v[52:55], v[4:5], off offset:64
	global_load_dwordx4 v[56:59], v[2:3], off offset:2048
	global_load_dwordx4 v[60:63], v[4:5], off offset:96
	v_lshl_add_u64 v[2:3], v[112:113], 1, s[4:5]
	s_mov_b64 s[4:5], 0x2080
	v_lshl_add_u64 v[4:5], v[2:3], 0, s[4:5]
	v_add_co_u32_e32 v6, vcc, s10, v2
	s_mov_b64 s[4:5], 0x4280
	s_nop 0
	v_addc_co_u32_e32 v7, vcc, 0, v3, vcc
	v_lshl_add_u64 v[8:9], v[2:3], 0, s[4:5]
	s_movk_i32 s4, 0x4000
	v_add_co_u32_e32 v10, vcc, s4, v2
	s_mov_b64 s[4:5], 0x6480
	s_nop 0
	v_addc_co_u32_e32 v11, vcc, 0, v3, vcc
	global_load_dwordx2 v[6:7], v[6:7], off offset:128
	s_nop 0
	global_load_dwordx2 v[10:11], v[10:11], off offset:640
	s_nop 0
	global_load_dwordx2 v[8:9], v[8:9], off offset:16
	s_nop 0
	global_load_dwordx2 v[4:5], v[4:5], off offset:16
	v_lshl_add_u64 v[12:13], v[2:3], 0, s[4:5]
	s_movk_i32 s4, 0x6000
	v_add_co_u32_e32 v14, vcc, s4, v2
	s_mov_b64 s[4:5], 0x8680
	s_nop 0
	v_addc_co_u32_e32 v15, vcc, 0, v3, vcc
	v_lshl_add_u64 v[16:17], v[2:3], 0, s[4:5]
	s_mov_b32 s5, 0x8000
	v_mad_u64_u32 v[0:1], s[0:1], v18, s11, v[0:1]
	v_add_co_u32_e32 v2, vcc, s5, v2
	v_mad_i32_i24 v1, v19, s11, v1
	v_mov_b32_e32 v131, v183
	v_addc_co_u32_e32 v3, vcc, 0, v3, vcc
	v_lshl_add_u64 v[0:1], v[0:1], 0, v[130:131]
	s_mov_b32 s0, 0x79000
	global_load_dwordx2 v[14:15], v[14:15], off offset:1152
	s_nop 0
	global_load_dwordx2 v[2:3], v[2:3], off offset:1664
	s_nop 0
	global_load_dwordx2 v[16:17], v[16:17], off offset:16
	s_nop 0
	global_load_dwordx2 v[12:13], v[12:13], off offset:16
	v_add_co_u32_e32 v18, vcc, s0, v0
	s_mov_b32 s0, 0x68000
	s_nop 0
	v_addc_co_u32_e32 v19, vcc, 0, v1, vcc
	v_add_co_u32_e32 v20, vcc, s0, v0
	s_mov_b32 s0, 0x57000
	s_nop 0
	v_addc_co_u32_e32 v21, vcc, 0, v1, vcc
	global_load_dwordx4 v[92:95], v[18:19], off
	global_load_dwordx4 v[84:87], v[20:21], off
	v_add_co_u32_e32 v18, vcc, s0, v0
	s_mov_b32 s0, 0x46000
	s_nop 0
	v_addc_co_u32_e32 v19, vcc, 0, v1, vcc
	v_add_co_u32_e32 v20, vcc, s0, v0
	s_mov_b32 s0, 0
	s_nop 0
	v_addc_co_u32_e32 v21, vcc, 0, v1, vcc
	global_load_dwordx4 v[88:91], v[18:19], off
	global_load_dwordx4 v[76:79], v[20:21], off
	v_add_co_u32_e32 v18, vcc, 0x35000, v0
	v_lshl_add_u64 v[132:133], v[0:1], 0, s[14:15]
	s_nop 0
	v_addc_co_u32_e32 v19, vcc, 0, v1, vcc
	v_add_co_u32_e32 v20, vcc, 0x24000, v0
	s_nop 1
	v_addc_co_u32_e32 v21, vcc, 0, v1, vcc
	global_load_dwordx4 v[80:83], v[18:19], off
	global_load_dwordx4 v[68:71], v[20:21], off
	v_add_co_u32_e32 v18, vcc, 0x13000, v0
	s_nop 1
	v_addc_co_u32_e32 v19, vcc, 0, v1, vcc
	v_add_co_u32_e32 v20, vcc, 0x2000, v0
	s_nop 1
	v_addc_co_u32_e32 v21, vcc, 0, v1, vcc
	global_load_dwordx4 v[72:75], v[18:19], off
	global_load_dwordx4 v[64:67], v[20:21], off
	s_waitcnt vmcnt(15)
	v_lshlrev_b32_e32 v18, 16, v6
	v_and_b32_e32 v6, 0xffff0000, v6
	v_mul_f32_e32 v217, 0x3d000000, v6
	v_lshlrev_b32_e32 v6, 16, v7
	v_mul_f32_e32 v218, 0x3d000000, v6
	v_and_b32_e32 v6, 0xffff0000, v7
	v_mul_f32_e32 v219, 0x3d000000, v6
	s_waitcnt vmcnt(12)
	v_lshlrev_b32_e32 v6, 16, v4
	v_and_b32_e32 v4, 0xffff0000, v4
	v_mul_f32_e32 v221, 0x3d000000, v4
	v_lshlrev_b32_e32 v4, 16, v5
	v_mul_f32_e32 v222, 0x3d000000, v4
	v_and_b32_e32 v4, 0xffff0000, v5
	v_mul_f32_e32 v223, 0x3d000000, v4
	v_lshlrev_b32_e32 v4, 16, v10
	v_mul_f32_e32 v224, 0x3d000000, v4
	v_and_b32_e32 v4, 0xffff0000, v10
	v_mul_f32_e32 v225, 0x3d000000, v4
	v_lshlrev_b32_e32 v4, 16, v11
	v_mul_f32_e32 v226, 0x3d000000, v4
	v_and_b32_e32 v4, 0xffff0000, v11
	v_mul_f32_e32 v227, 0x3d000000, v4
	v_lshlrev_b32_e32 v4, 16, v8
	v_mul_f32_e32 v228, 0x3d000000, v4
	v_and_b32_e32 v4, 0xffff0000, v8
	v_mul_f32_e32 v229, 0x3d000000, v4
	v_lshlrev_b32_e32 v4, 16, v9
	v_mul_f32_e32 v230, 0x3d000000, v4
	v_and_b32_e32 v4, 0xffff0000, v9
	v_mul_f32_e32 v231, 0x3d000000, v4
	s_waitcnt vmcnt(11)
	v_lshlrev_b32_e32 v4, 16, v14
	v_mul_f32_e32 v232, 0x3d000000, v4
	v_and_b32_e32 v4, 0xffff0000, v14
	v_mul_f32_e32 v233, 0x3d000000, v4
	v_lshlrev_b32_e32 v4, 16, v15
	v_mul_f32_e32 v234, 0x3d000000, v4
	v_and_b32_e32 v4, 0xffff0000, v15
	v_mul_f32_e32 v235, 0x3d000000, v4
	s_waitcnt vmcnt(8)
	v_lshlrev_b32_e32 v4, 16, v12
	v_mul_f32_e32 v236, 0x3d000000, v4
	v_and_b32_e32 v4, 0xffff0000, v12
	v_mul_f32_e32 v237, 0x3d000000, v4
	v_lshlrev_b32_e32 v4, 16, v13
	v_mul_f32_e32 v238, 0x3d000000, v4
	v_and_b32_e32 v4, 0xffff0000, v13
	v_mul_f32_e32 v239, 0x3d000000, v4
	v_lshlrev_b32_e32 v4, 16, v2
	v_and_b32_e32 v2, 0xffff0000, v2
	v_mul_f32_e32 v241, 0x3d000000, v2
	v_lshlrev_b32_e32 v2, 16, v3
	v_mul_f32_e32 v242, 0x3d000000, v2
	v_and_b32_e32 v2, 0xffff0000, v3
	v_mul_f32_e32 v243, 0x3d000000, v2
	v_lshlrev_b32_e32 v2, 16, v16
	v_mul_f32_e32 v244, 0x3d000000, v2
	v_and_b32_e32 v2, 0xffff0000, v16
	v_mul_f32_e32 v245, 0x3d000000, v2
	v_lshlrev_b32_e32 v2, 16, v17
	v_mul_f32_e32 v246, 0x3d000000, v2
	v_and_b32_e32 v2, 0xffff0000, v17
	v_mul_f32_e32 v247, 0x3d000000, v2
	v_lshl_add_u64 v[2:3], s[2:3], 0, v[106:107]
	v_lshlrev_b64 v[2:3], 14, v[2:3]
	v_mul_f32_e32 v131, 0x3d000000, v18
	v_mul_f32_e32 v220, 0x3d000000, v6
	v_mul_f32_e32 v240, 0x3d000000, v4
	v_lshl_add_u64 v[134:135], v[126:127], 0, v[2:3]
; #define LAS __attribute__((address_space(3)))
; #define LDS_WAIT() asm volatile("s_waitcnt lgkmcnt(0)" ::: "memory")
; __device__ __forceinline__ void idx_unit(bf16* QB, float* SC, int* SEL, const float* qg, const float* kg, int b, int tp, LAS unsigned char* wl, int lane, bool do_norm) {
;     ...
;         for (int s0 = 0; s0 < ce; s0 += 64) {
; #pragma unroll
;             for (int i = 0; i < 8; ++i) *(LAS bf16x8*)(sdst + (8 * i) * 144) = cur[i];
;             const int sn = (s0 + 64 < ce) ? s0 + 64 : 0;
; #pragma unroll
;             for (int i = 0; i < 8; ++i) cur[i] = *(const bf16x8*)(kg8 + (size_t)(sn + 8 * i) * NBP);
;             LDS_WAIT();
; #pragma unroll
;             for (int tt = 0; tt < 2; ++tt) {
;                 f32x16 acc0, acc1;
; #pragma unroll
;                 for (int r = 0; r < 16; ++r) { acc0[r] = 0.f; acc1[r] = 0.f; }
; #pragma unroll
;                 for (int ks = 0; ks < 4; ++ks) { const bf16x8 bfr = *(const LAS bf16x8*)(fsrc + tt * 32 * 144 + 32 * ks);
;                     acc0 = __builtin_amdgcn_mfma_f32_32x32x16_bf16(af[0][ks], bfr, acc0, 0, 0, 0); acc1 = __builtin_amdgcn_mfma_f32_32x32x16_bf16(af[1][ks], bfr, acc1, 0, 0, 0); }
;                 float pa = 0.f, pb = 0.f, pc = 0.f, pd = 0.f;
; #pragma unroll
;                 for (int r = 0; r < 8; ++r) { pa += w[0][r] * (__builtin_fmaxf(acc0[r], 0.f) * 0.125f); pb += w[1][r] * (__builtin_fmaxf(acc0[8 + r], 0.f) * 0.125f);
;                                               pc += w[2][r] * (__builtin_fmaxf(acc1[r], 0.f) * 0.125f); pd += w[3][r] * (__builtin_fmaxf(acc1[8 + r], 0.f) * 0.125f); }
;                 const float snd0 = hi ? pa : pb, snd1 = hi ? pc : pd; const float rcv0 = __shfl_xor(snd0, 32), rcv1 = __shfl_xor(snd1, 32);
.LBB0_243:
	s_add_i32 s3, s0, 64
	s_cmp_lt_i32 s0, s7
	s_cselect_b64 s[0:1], -1, 0
	s_and_b64 vcc, s[0:1], exec
	s_cselect_b32 s4, s3, 0
	v_mad_u64_u32 v[0:1], s[0:1], s4, v212, v[132:133]
	s_waitcnt vmcnt(0)
	ds_write_b128 v101, v[64:67]
	ds_write_b128 v101, v[72:75] offset:1152
	ds_write_b128 v101, v[68:71] offset:2304
	ds_write_b128 v101, v[80:83] offset:3456
	ds_write_b128 v101, v[76:79] offset:4608
	ds_write_b128 v101, v[88:91] offset:5760
	ds_write_b128 v101, v[84:87] offset:6912
	ds_write_b128 v101, v[92:95] offset:8064
	s_or_b32 s0, s4, 8
	global_load_dwordx4 v[64:67], v[0:1], off
	v_mad_u64_u32 v[0:1], s[0:1], s0, v212, v[132:133]
	s_or_b32 s0, s4, 16
	global_load_dwordx4 v[72:75], v[0:1], off
	v_mad_u64_u32 v[0:1], s[0:1], s0, v212, v[132:133]
	s_or_b32 s0, s4, 24
	global_load_dwordx4 v[68:71], v[0:1], off
	v_mad_u64_u32 v[0:1], s[0:1], s0, v212, v[132:133]
	s_or_b32 s0, s4, 32
	global_load_dwordx4 v[80:83], v[0:1], off
	v_mad_u64_u32 v[0:1], s[0:1], s0, v212, v[132:133]
	s_or_b32 s0, s4, 40
	global_load_dwordx4 v[76:79], v[0:1], off
	v_mad_u64_u32 v[0:1], s[0:1], s0, v212, v[132:133]
	s_or_b32 s0, s4, 48
	global_load_dwordx4 v[88:91], v[0:1], off
	v_mad_u64_u32 v[0:1], s[0:1], s0, v212, v[132:133]
	s_or_b32 s0, s4, 56
	global_load_dwordx4 v[84:87], v[0:1], off
	v_mad_u64_u32 v[0:1], s[0:1], s0, v212, v[132:133]
	global_load_dwordx4 v[92:95], v[0:1], off
	s_waitcnt lgkmcnt(0)
	ds_read_b128 v[138:141], v103
	ds_read_b128 v[142:145], v103 offset:32
	ds_read_b128 v[146:149], v103 offset:64
	ds_read_b128 v[150:153], v103 offset:96
	s_waitcnt lgkmcnt(3)
	v_mfma_f32_32x32x16_bf16 v[16:31], v[40:43], v[138:141], 0
	v_add_co_u32_e64 v136, s[0:1], s5, v134
	s_nop 1
	v_addc_co_u32_e64 v137, s[0:1], 0, v135, s[0:1]
	s_mov_b64 s[0:1], 0x100
	v_mfma_f32_32x32x16_bf16 v[0:15], v[56:59], v[138:141], 0
	s_waitcnt lgkmcnt(2)
	v_mfma_f32_32x32x16_bf16 v[0:15], v[48:51], v[142:145], v[0:15]
	v_mfma_f32_32x32x16_bf16 v[16:31], v[32:35], v[142:145], v[16:31]
	s_waitcnt lgkmcnt(1)
	v_mfma_f32_32x32x16_bf16 v[0:15], v[52:55], v[146:149], v[0:15]
	v_mfma_f32_32x32x16_bf16 v[16:31], v[36:39], v[146:149], v[16:31]
	s_waitcnt lgkmcnt(0)
	v_mfma_f32_32x32x16_bf16 v[0:15], v[60:63], v[150:153], v[0:15]
	v_mfma_f32_32x32x16_bf16 v[16:31], v[44:47], v[150:153], v[16:31]
	ds_read_b128 v[154:157], v103 offset:4608
	ds_read_b128 v[158:161], v103 offset:4640
	ds_read_b128 v[162:165], v103 offset:4672
	ds_read_b128 v[166:169], v103 offset:4704
	s_nop 10
	v_max_f32_e32 v0, 0, v0
	v_max_f32_e32 v1, 0, v1
	v_fma_f32 v0, v232, v0, 0
	v_max_f32_e32 v8, 0, v8
	v_fmac_f32_e32 v0, v233, v1
	v_max_f32_e32 v1, 0, v9
	v_max_f32_e32 v16, 0, v16
	v_fma_f32 v8, v240, v8, 0
	v_max_f32_e32 v17, 0, v17
	v_fmac_f32_e32 v8, v241, v1
	v_fma_f32 v16, v131, v16, 0
	v_max_f32_e32 v1, 0, v18
	v_max_f32_e32 v24, 0, v24
	v_fmac_f32_e32 v16, v217, v17
	v_max_f32_e32 v17, 0, v25
	v_fmac_f32_e32 v16, v218, v1
	v_fma_f32 v24, v224, v24, 0
	v_max_f32_e32 v1, 0, v26
	v_fmac_f32_e32 v24, v225, v17
	v_fmac_f32_e32 v24, v226, v1
	v_max_f32_e32 v1, 0, v2
	v_fmac_f32_e32 v0, v234, v1
	v_max_f32_e32 v1, 0, v10
	v_fmac_f32_e32 v8, v242, v1
	v_max_f32_e32 v1, 0, v19
	v_fmac_f32_e32 v16, v219, v1
	v_max_f32_e32 v1, 0, v27
	v_fmac_f32_e32 v24, v227, v1
	v_max_f32_e32 v1, 0, v3
	v_fmac_f32_e32 v0, v235, v1
	v_max_f32_e32 v1, 0, v11
	v_fmac_f32_e32 v8, v243, v1
	v_max_f32_e32 v1, 0, v20
	v_fmac_f32_e32 v16, v220, v1
	v_max_f32_e32 v1, 0, v28
	v_fmac_f32_e32 v24, v228, v1
	v_max_f32_e32 v1, 0, v4
	v_fmac_f32_e32 v0, v236, v1
	v_max_f32_e32 v1, 0, v12
	v_fmac_f32_e32 v8, v244, v1
	v_max_f32_e32 v1, 0, v21
	v_fmac_f32_e32 v16, v221, v1
	v_max_f32_e32 v1, 0, v29
	v_fmac_f32_e32 v24, v229, v1
	v_max_f32_e32 v1, 0, v5
	v_fmac_f32_e32 v0, v237, v1
	v_max_f32_e32 v1, 0, v13
	v_fmac_f32_e32 v8, v245, v1
	v_max_f32_e32 v1, 0, v22
	v_fmac_f32_e32 v16, v222, v1
	v_max_f32_e32 v1, 0, v30
	v_fmac_f32_e32 v24, v230, v1
	v_max_f32_e32 v1, 0, v6
	v_fmac_f32_e32 v0, v238, v1
	v_max_f32_e32 v1, 0, v14
	v_fmac_f32_e32 v8, v246, v1
	v_max_f32_e32 v1, 0, v23
	v_fmac_f32_e32 v16, v223, v1
	v_max_f32_e32 v1, 0, v31
	v_fmac_f32_e32 v24, v231, v1
	v_max_f32_e32 v1, 0, v7
	v_fmac_f32_e32 v0, v239, v1
	v_max_f32_e32 v1, 0, v15
	v_fmac_f32_e32 v8, v247, v1
	v_cndmask_b32_e64 v1, v16, v24, s[40:41]
	v_cndmask_b32_e64 v2, v0, v8, s[40:41]
	ds_bpermute_b32 v1, v97, v1
	ds_bpermute_b32 v2, v97, v2
	v_cndmask_b32_e64 v3, v24, v16, s[40:41]
	v_cndmask_b32_e64 v0, v8, v0, s[40:41]
	s_waitcnt lgkmcnt(1)
	v_add_f32_e32 v1, v3, v1
	s_waitcnt lgkmcnt(0)
; #define LAS __attribute__((address_space(3)))
; __device__ __forceinline__ void idx_unit(bf16* QB, float* SC, int* SEL, const float* qg, const float* kg, int b, int tp, LAS unsigned char* wl, int lane, bool do_norm) {
;     ...
;             for (int tt = 0; tt < 2; ++tt) {
;                 f32x16 acc0, acc1;
; #pragma unroll
;                 for (int r = 0; r < 16; ++r) { acc0[r] = 0.f; acc1[r] = 0.f; }
; #pragma unroll
;                 for (int ks = 0; ks < 4; ++ks) { const bf16x8 bfr = *(const LAS bf16x8*)(fsrc + tt * 32 * 144 + 32 * ks);
;                     acc0 = __builtin_amdgcn_mfma_f32_32x32x16_bf16(af[0][ks], bfr, acc0, 0, 0, 0); acc1 = __builtin_amdgcn_mfma_f32_32x32x16_bf16(af[1][ks], bfr, acc1, 0, 0, 0); }
;                 float pa = 0.f, pb = 0.f, pc = 0.f, pd = 0.f;
; #pragma unroll
;                 for (int r = 0; r < 8; ++r) { pa += w[0][r] * (__builtin_fmaxf(acc0[r], 0.f) * 0.125f); pb += w[1][r] * (__builtin_fmaxf(acc0[8 + r], 0.f) * 0.125f);
;                                               pc += w[2][r] * (__builtin_fmaxf(acc1[r], 0.f) * 0.125f); pd += w[3][r] * (__builtin_fmaxf(acc1[8 + r], 0.f) * 0.125f); }
;                 const float snd0 = hi ? pa : pb, snd1 = hi ? pc : pd; const float rcv0 = __shfl_xor(snd0, 32), rcv1 = __shfl_xor(snd1, 32);
;                 scw0[s0 + 32 * tt] = (hi ? pb : pa) + rcv0;
;                 scw1[s0 + 32 * tt] = (hi ? pd : pc) + rcv1;
;             }
;     ...
;         for (int a = 0; a < 4; ++a) select_query(SC + (row + a) * SEQ, SEL + (row + a) * 256, ce, lane);
	v_add_f32_e32 v0, v0, v2
	global_store_dword v[134:135], v1, off
	global_store_dword v[136:137], v0, off
	v_mfma_f32_32x32x16_bf16 v[16:31], v[40:43], v[154:157], 0
	v_mfma_f32_32x32x16_bf16 v[0:15], v[56:59], v[154:157], 0
	v_mfma_f32_32x32x16_bf16 v[0:15], v[48:51], v[158:161], v[0:15]
	v_mfma_f32_32x32x16_bf16 v[16:31], v[32:35], v[158:161], v[16:31]
	v_mfma_f32_32x32x16_bf16 v[0:15], v[52:55], v[162:165], v[0:15]
	v_mfma_f32_32x32x16_bf16 v[16:31], v[36:39], v[162:165], v[16:31]
	v_mfma_f32_32x32x16_bf16 v[0:15], v[60:63], v[166:169], v[0:15]
	v_mfma_f32_32x32x16_bf16 v[16:31], v[44:47], v[166:169], v[16:31]
	s_nop 10
	v_max_f32_e32 v0, 0, v0
	v_max_f32_e32 v1, 0, v1
	v_fma_f32 v0, v232, v0, 0
	v_max_f32_e32 v8, 0, v8
	v_fmac_f32_e32 v0, v233, v1
	v_max_f32_e32 v1, 0, v9
	v_max_f32_e32 v16, 0, v16
	v_fma_f32 v8, v240, v8, 0
	v_max_f32_e32 v17, 0, v17
	v_fmac_f32_e32 v8, v241, v1
	v_fma_f32 v16, v131, v16, 0
	v_max_f32_e32 v1, 0, v18
	v_max_f32_e32 v24, 0, v24
	v_fmac_f32_e32 v16, v217, v17
	v_max_f32_e32 v17, 0, v25
	v_fmac_f32_e32 v16, v218, v1
	v_fma_f32 v24, v224, v24, 0
	v_max_f32_e32 v1, 0, v26
	v_fmac_f32_e32 v24, v225, v17
	v_fmac_f32_e32 v24, v226, v1
	v_max_f32_e32 v1, 0, v2
	v_fmac_f32_e32 v0, v234, v1
	v_max_f32_e32 v1, 0, v10
	v_fmac_f32_e32 v8, v242, v1
	v_max_f32_e32 v1, 0, v19
	v_fmac_f32_e32 v16, v219, v1
	v_max_f32_e32 v1, 0, v27
	v_fmac_f32_e32 v24, v227, v1
	v_max_f32_e32 v1, 0, v3
	v_fmac_f32_e32 v0, v235, v1
	v_max_f32_e32 v1, 0, v11
	v_fmac_f32_e32 v8, v243, v1
	v_max_f32_e32 v1, 0, v20
	v_fmac_f32_e32 v16, v220, v1
	v_max_f32_e32 v1, 0, v28
	v_fmac_f32_e32 v24, v228, v1
	v_max_f32_e32 v1, 0, v4
	v_fmac_f32_e32 v0, v236, v1
	v_max_f32_e32 v1, 0, v12
	v_fmac_f32_e32 v8, v244, v1
	v_max_f32_e32 v1, 0, v21
	v_fmac_f32_e32 v16, v221, v1
	v_max_f32_e32 v1, 0, v29
	v_fmac_f32_e32 v24, v229, v1
	v_max_f32_e32 v1, 0, v5
	v_fmac_f32_e32 v0, v237, v1
	v_max_f32_e32 v1, 0, v13
	v_fmac_f32_e32 v8, v245, v1
	v_max_f32_e32 v1, 0, v22
	v_fmac_f32_e32 v16, v222, v1
	v_max_f32_e32 v1, 0, v30
	v_fmac_f32_e32 v24, v230, v1
	v_max_f32_e32 v1, 0, v6
	v_fmac_f32_e32 v0, v238, v1
	v_max_f32_e32 v1, 0, v14
	v_fmac_f32_e32 v8, v246, v1
	v_max_f32_e32 v1, 0, v23
	v_fmac_f32_e32 v16, v223, v1
	v_max_f32_e32 v1, 0, v31
	v_fmac_f32_e32 v24, v231, v1
	v_max_f32_e32 v1, 0, v7
	v_fmac_f32_e32 v0, v239, v1
	v_max_f32_e32 v1, 0, v15
	v_fmac_f32_e32 v8, v247, v1
	v_cndmask_b32_e64 v1, v16, v24, s[40:41]
	v_cndmask_b32_e64 v2, v0, v8, s[40:41]
	ds_bpermute_b32 v1, v97, v1
	ds_bpermute_b32 v2, v97, v2
	v_cndmask_b32_e64 v3, v24, v16, s[40:41]
	v_cndmask_b32_e64 v0, v8, v0, s[40:41]
	s_waitcnt lgkmcnt(1)
	v_add_f32_e32 v1, v3, v1
	s_waitcnt lgkmcnt(0)
	v_add_f32_e32 v0, v0, v2
	global_store_dword v[134:135], v1, off offset:128
	global_store_dword v[136:137], v0, off offset:128
	s_waitcnt lgkmcnt(0)
	v_lshl_add_u64 v[134:135], v[134:135], 0, s[0:1]
	s_mov_b32 s0, s3
	s_cbranch_vccnz .LBB0_243
	v_add_u32_e32 v138, 0x180, v96
	v_add_u32_e32 v139, 0x1c0, v96
	v_add_u32_e32 v140, 0x200, v96
	v_add_u32_e32 v141, 0x240, v96
	v_add_u32_e32 v142, 0x280, v96
	v_add_u32_e32 v143, 0x2c0, v96
	v_add_u32_e32 v144, 0x300, v96
	v_add_u32_e32 v145, 0x340, v96
	v_add_u32_e32 v146, 0x380, v96
	v_add_u32_e32 v147, 0x3c0, v96
	v_add_u32_e32 v148, 0x400, v96
	v_add_u32_e32 v149, 0x440, v96
	v_add_u32_e32 v150, 0x480, v96
	v_add_u32_e32 v151, 0x4c0, v96
	v_add_u32_e32 v152, 0x500, v96
	v_add_u32_e32 v153, 0x540, v96
	v_add_u32_e32 v154, 0x580, v96
	v_add_u32_e32 v155, 0x5c0, v96
	v_add_u32_e32 v156, 0x600, v96
	v_add_u32_e32 v157, 0x640, v96
	v_add_u32_e32 v158, 0x680, v96
	v_add_u32_e32 v159, 0x6c0, v96
	v_add_u32_e32 v160, 0x700, v96
	v_add_u32_e32 v161, 0x740, v96
	v_add_u32_e32 v162, 0x780, v96
	v_add_u32_e32 v163, 0x7c0, v96
	v_add_u32_e32 v164, 0x800, v96
	v_add_u32_e32 v165, 0x840, v96
	v_add_u32_e32 v166, 0x880, v96
	v_add_u32_e32 v167, 0x8c0, v96
	v_add_u32_e32 v168, 0x900, v96
	v_add_u32_e32 v169, 0x940, v96
	s_cmpk_gt_u32 s6, 0x23f
	s_cselect_b64 s[84:85], -1, 0
	s_cmpk_gt_u32 s6, 0x43f
	s_cselect_b64 s[86:87], -1, 0
	s_cmpk_gt_u32 s6, 0x63f
	s_cselect_b64 s[88:89], -1, 0
	s_cmpk_gt_u32 s6, 0x83f
	s_cselect_b64 s[90:91], -1, 0
	s_cmpk_gt_u32 s6, 0xa3f
	s_cselect_b64 s[92:93], -1, 0
	s_cmpk_gt_u32 s6, 0xc3f
	s_cselect_b64 s[94:95], -1, 0
	s_cmpk_gt_u32 s6, 0xe3f
	s_cselect_b64 s[96:97], -1, 0
	s_cmpk_gt_u32 s6, 0x17f
	s_cselect_b64 s[0:1], -1, 0
	v_writelane_b32 v254, s0, 7
	s_cmpk_gt_u32 s6, 0x1bf
	s_nop 0
	v_writelane_b32 v254, s1, 8
	s_cselect_b64 s[0:1], -1, 0
	v_writelane_b32 v254, s0, 9
	s_cmpk_gt_u32 s6, 0x1ff
	s_waitcnt vmcnt(0)
; __device__ __forceinline__ unsigned fkey(float f) { const unsigned u = __builtin_bit_cast(unsigned, f); return (u & 0x80000000u) ? ~u : (u | 0x80000000u); }
; __device__ __forceinline__ void select_query(const float* sc, int* sel, int ce, int lane) {
;     const int nreg = ce >> 6;
;     unsigned key[64];
;     {
;         float raw[64];
; #pragma unroll
;         for (int g = 0; g < 8; ++g) {
;             if (8 * g < nreg) {
; #pragma unroll
;                 for (int j = 8 * g; j < 8 * g + 8; ++j) raw[j] = sc[lane + 64 * j];
;             } else {
; #pragma unroll
;                 for (int j = 8 * g; j < 8 * g + 8; ++j) raw[j] = 0.f;
;             }
;         }
; #pragma unroll
;         for (int j = 0; j < 64; ++j) key[j] = (j < nreg) ? fkey(raw[j]) : 0u;
	s_mov_b32 s3, 0
	v_writelane_b32 v254, s1, 10
	s_cselect_b64 s[0:1], -1, 0
	v_writelane_b32 v254, s0, 11
	s_cmpk_gt_u32 s6, 0x27f
	s_nop 0
	v_writelane_b32 v254, s1, 12
	s_cselect_b64 s[0:1], -1, 0
	v_writelane_b32 v254, s0, 13
	s_cmpk_gt_u32 s6, 0x2bf
	s_nop 0
	v_writelane_b32 v254, s1, 14
	s_cselect_b64 s[0:1], -1, 0
	v_writelane_b32 v254, s0, 15
	s_cmpk_gt_u32 s6, 0x2ff
	s_nop 0
	v_writelane_b32 v254, s1, 16
	s_cselect_b64 s[0:1], -1, 0
	v_writelane_b32 v254, s0, 17
	s_cmpk_gt_u32 s6, 0x33f
	s_nop 0
	v_writelane_b32 v254, s1, 18
	s_cselect_b64 s[0:1], -1, 0
	v_writelane_b32 v254, s0, 19
	s_cmpk_gt_u32 s6, 0x37f
	s_nop 0
	v_writelane_b32 v254, s1, 20
	s_cselect_b64 s[0:1], -1, 0
	v_writelane_b32 v254, s0, 21
	s_cmpk_gt_u32 s6, 0x3bf
	s_nop 0
	v_writelane_b32 v254, s1, 22
	s_cselect_b64 s[0:1], -1, 0
	v_writelane_b32 v254, s0, 23
	s_cmpk_gt_u32 s6, 0x3ff
	s_nop 0
	v_writelane_b32 v254, s1, 24
	s_cselect_b64 s[0:1], -1, 0
	v_writelane_b32 v254, s0, 25
	s_cmpk_gt_u32 s6, 0x47f
	s_nop 0
	v_writelane_b32 v254, s1, 26
	s_cselect_b64 s[0:1], -1, 0
	v_writelane_b32 v254, s0, 27
	s_cmpk_gt_u32 s6, 0x4bf
	s_nop 0
	v_writelane_b32 v254, s1, 28
	s_cselect_b64 s[0:1], -1, 0
	v_writelane_b32 v254, s0, 29
	s_cmpk_gt_u32 s6, 0x4ff
	s_nop 0
	v_writelane_b32 v254, s1, 30
	s_cselect_b64 s[0:1], -1, 0
	v_writelane_b32 v254, s0, 31
	s_cmpk_gt_u32 s6, 0x53f
	s_nop 0
	v_writelane_b32 v254, s1, 32
	s_cselect_b64 s[0:1], -1, 0
	v_writelane_b32 v254, s0, 33
	s_cmpk_gt_u32 s6, 0x57f
	s_nop 0
	v_writelane_b32 v254, s1, 34
	s_cselect_b64 s[0:1], -1, 0
	v_writelane_b32 v254, s0, 35
	s_cmpk_gt_u32 s6, 0x5bf
	s_nop 0
	v_writelane_b32 v254, s1, 36
	s_cselect_b64 s[0:1], -1, 0
	v_writelane_b32 v254, s0, 37
	s_cmpk_gt_u32 s6, 0x5ff
	s_nop 0
	v_writelane_b32 v254, s1, 38
	s_cselect_b64 s[0:1], -1, 0
	v_writelane_b32 v254, s0, 39
	s_cmpk_gt_u32 s6, 0x67f
	s_nop 0
	v_writelane_b32 v254, s1, 40
	s_cselect_b64 s[0:1], -1, 0
	v_writelane_b32 v254, s0, 41
	s_cmpk_gt_u32 s6, 0x6bf
	s_nop 0
	v_writelane_b32 v254, s1, 42
	s_cselect_b64 s[0:1], -1, 0
	v_writelane_b32 v254, s0, 43
	s_cmpk_gt_u32 s6, 0x6ff
	s_nop 0
	v_writelane_b32 v254, s1, 44
	s_cselect_b64 s[0:1], -1, 0
	v_writelane_b32 v254, s0, 45
	s_cmpk_gt_u32 s6, 0x73f
	s_nop 0
	v_writelane_b32 v254, s1, 46
	s_cselect_b64 s[0:1], -1, 0
	v_writelane_b32 v254, s0, 47
	s_cmpk_gt_u32 s6, 0x77f
	s_nop 0
	v_writelane_b32 v254, s1, 48
	s_cselect_b64 s[0:1], -1, 0
	v_writelane_b32 v254, s0, 49
	s_cmpk_gt_u32 s6, 0x7bf
	s_nop 0
	v_writelane_b32 v254, s1, 50
	s_cselect_b64 s[0:1], -1, 0
	v_writelane_b32 v254, s0, 51
	s_cmpk_gt_u32 s6, 0x7ff
	s_nop 0
	v_writelane_b32 v254, s1, 52
	s_cselect_b64 s[0:1], -1, 0
	v_writelane_b32 v254, s0, 53
	s_cmpk_gt_u32 s6, 0x87f
	s_nop 0
	v_writelane_b32 v254, s1, 54
	s_cselect_b64 s[0:1], -1, 0
	v_writelane_b32 v254, s0, 55
	s_cmpk_gt_u32 s6, 0x8bf
	s_nop 0
	v_writelane_b32 v254, s1, 56
	s_cselect_b64 s[0:1], -1, 0
	v_writelane_b32 v254, s0, 57
	s_cmpk_gt_u32 s6, 0x8ff
	s_nop 0
	v_writelane_b32 v254, s1, 58
	s_cselect_b64 s[0:1], -1, 0
	v_writelane_b32 v254, s0, 59
	s_cmpk_gt_u32 s6, 0x93f
	s_nop 0
	v_writelane_b32 v254, s1, 60
	s_cselect_b64 s[0:1], -1, 0
	v_writelane_b32 v254, s0, 61
	s_cmpk_gt_u32 s6, 0x97f
	s_nop 0
	v_writelane_b32 v254, s1, 62
	s_cselect_b64 s[0:1], -1, 0
	v_writelane_b32 v254, s0, 63
	s_cmpk_gt_u32 s6, 0x9bf
	s_nop 0
	v_writelane_b32 v250, s1, 0
	s_cselect_b64 s[0:1], -1, 0
	v_writelane_b32 v250, s0, 1
	s_cmpk_gt_u32 s6, 0x9ff
	s_nop 0
	v_writelane_b32 v250, s1, 2
	s_cselect_b64 s[0:1], -1, 0
	v_writelane_b32 v250, s0, 3
	s_cmpk_gt_u32 s6, 0xa7f
	s_nop 0
	v_writelane_b32 v250, s1, 4
	s_cselect_b64 s[0:1], -1, 0
	v_writelane_b32 v250, s0, 5
	s_cmpk_gt_u32 s6, 0xabf
	s_nop 0
	v_writelane_b32 v250, s1, 6
	s_cselect_b64 s[0:1], -1, 0
	v_writelane_b32 v250, s0, 7
	s_cmpk_gt_u32 s6, 0xaff
	s_nop 0
	v_writelane_b32 v250, s1, 8
	s_cselect_b64 s[0:1], -1, 0
	v_writelane_b32 v250, s0, 9
	s_cmpk_gt_u32 s6, 0xb3f
	s_nop 0
	v_writelane_b32 v250, s1, 10
	s_cselect_b64 s[0:1], -1, 0
	v_writelane_b32 v250, s0, 11
	s_cmpk_gt_u32 s6, 0xb7f
	s_nop 0
	v_writelane_b32 v250, s1, 12
	s_cselect_b64 s[0:1], -1, 0
	v_writelane_b32 v250, s0, 13
	s_cmpk_gt_u32 s6, 0xbbf
	s_nop 0
	v_writelane_b32 v250, s1, 14
	s_cselect_b64 s[0:1], -1, 0
	v_writelane_b32 v250, s0, 15
	s_cmpk_gt_u32 s6, 0xbff
	s_nop 0
	v_writelane_b32 v250, s1, 16
	s_cselect_b64 s[0:1], -1, 0
	v_writelane_b32 v250, s0, 17
	s_cmpk_gt_u32 s6, 0xc7f
	s_nop 0
	v_writelane_b32 v250, s1, 18
	s_cselect_b64 s[0:1], -1, 0
	v_writelane_b32 v250, s0, 19
	s_cmpk_gt_u32 s6, 0xcbf
	s_nop 0
	v_writelane_b32 v250, s1, 20
	s_cselect_b64 s[0:1], -1, 0
	v_writelane_b32 v250, s0, 21
	s_cmpk_gt_u32 s6, 0xcff
	s_nop 0
	v_writelane_b32 v250, s1, 22
	s_cselect_b64 s[0:1], -1, 0
	v_writelane_b32 v250, s0, 23
	s_cmpk_gt_u32 s6, 0xd3f
	s_nop 0
	v_writelane_b32 v250, s1, 24
	s_cselect_b64 s[0:1], -1, 0
	v_writelane_b32 v250, s0, 25
	s_cmpk_gt_u32 s6, 0xd7f
	s_nop 0
	v_writelane_b32 v250, s1, 26
	s_cselect_b64 s[0:1], -1, 0
	v_writelane_b32 v250, s0, 27
	s_cmpk_gt_u32 s6, 0xdbf
	s_nop 0
	v_writelane_b32 v250, s1, 28
	s_cselect_b64 s[0:1], -1, 0
	v_writelane_b32 v250, s0, 29
	s_cmpk_gt_u32 s6, 0xdff
	s_nop 0
	v_writelane_b32 v250, s1, 30
	s_cselect_b64 s[0:1], -1, 0
	s_cmpk_gt_u32 s6, 0xe7f
	s_cselect_b64 s[36:37], -1, 0
	s_cmpk_gt_u32 s6, 0xebf
	s_cselect_b64 s[38:39], -1, 0
	s_cmpk_gt_u32 s6, 0xeff
	s_cselect_b64 s[42:43], -1, 0
	s_cmpk_gt_u32 s6, 0xf3f
	s_cselect_b64 s[44:45], -1, 0
	s_cmpk_gt_u32 s6, 0xf7f
	s_cselect_b64 s[46:47], -1, 0
	s_cmpk_gt_u32 s6, 0xfbf
	s_cselect_b64 s[48:49], -1, 0
	s_cmpk_gt_u32 s6, 0xfff
	v_writelane_b32 v250, s0, 31
	s_cselect_b64 s[50:51], -1, 0
	s_nop 0
	v_writelane_b32 v250, s1, 32
	s_branch .LBB0_247
